# prologue fence v1 plus sc1 write-through on the eight transposed-weight stores of the prologue (less dirty L2 at the fence)
# speedup vs baseline: 1.0116x; 1.0116x over previous
; __device__ __forceinline__ unsigned cvt_pk_bf16(float lo, float hi) { const f32x2 v = {lo, hi}; const bf16x2_t b = __builtin_convertvector(v, bf16x2_t); return __builtin_bit_cast(unsigned, b); }
; #define LAS __attribute__((address_space(3)))
; __device__ __forceinline__ void transpose_item(const float* W, int K, int N, const float* gain, bf16_t* WT, int k0, int n0, int drowA, int drowB, LAS float* scr, int lane) {
;     ...
;     for (int i = 0; i < 16; ++i) { LAS float* d = scr + (4 * i + (lane >> 4)) * 65 + 4 * (lane & 15); d[0] = v[i][0]; d[1] = v[i][1]; d[2] = v[i][2]; d[3] = v[i][3]; }
;     asm volatile("s_waitcnt lgkmcnt(0)" ::: "memory");
;     const int c = lane & 7;
; #pragma unroll
;     for (int j = 0; j < 8; ++j) { const int n = (lane >> 3) + 8 * j; const LAS float* s = scr + (8 * c) * 65 + n;
;         u32x4 o; o.x = pg8::cvt_pk_bf16(s[0 * 65], s[1 * 65]); o.y = pg8::cvt_pk_bf16(s[2 * 65], s[3 * 65]); o.z = pg8::cvt_pk_bf16(s[4 * 65], s[5 * 65]); o.w = pg8::cvt_pk_bf16(s[6 * 65], s[7 * 65]);
.LBB0_8:
	s_waitcnt vmcnt(15)
	ds_write2_b32 v78, v6, v7 offset1:1
	ds_write2_b32 v78, v8, v9 offset0:2 offset1:3
	v_add_u32_e32 v6, 0x410, v78
	s_waitcnt vmcnt(14)
	ds_write2_b32 v6, v2, v3 offset1:1
	v_add_u32_e32 v2, 0x418, v78
	ds_write2_b32 v2, v4, v5 offset1:1
	v_add_u32_e32 v2, 0x820, v78
	s_waitcnt vmcnt(13)
	ds_write2_b32 v2, v14, v15 offset1:1
	v_add_u32_e32 v2, 0x828, v78
	ds_write2_b32 v2, v16, v17 offset1:1
	v_add_u32_e32 v2, 0xc30, v78
	s_waitcnt vmcnt(12)
	ds_write2_b32 v2, v10, v11 offset1:1
	v_add_u32_e32 v2, 0xc38, v78
	ds_write2_b32 v2, v12, v13 offset1:1
	v_add_u32_e32 v2, 0x1040, v78
	s_waitcnt vmcnt(11)
	ds_write2_b32 v2, v22, v23 offset1:1
	v_add_u32_e32 v2, 0x1048, v78
	ds_write2_b32 v2, v24, v25 offset1:1
	v_add_u32_e32 v2, 0x1450, v78
	s_waitcnt vmcnt(10)
	ds_write2_b32 v2, v18, v19 offset1:1
	v_add_u32_e32 v2, 0x1458, v78
	ds_write2_b32 v2, v20, v21 offset1:1
	v_add_u32_e32 v2, 0x1860, v78
	s_waitcnt vmcnt(9)
	ds_write2_b32 v2, v30, v31 offset1:1
	v_add_u32_e32 v2, 0x1868, v78
	ds_write2_b32 v2, v32, v33 offset1:1
	v_add_u32_e32 v2, 0x1c70, v78
	s_waitcnt vmcnt(8)
	ds_write2_b32 v2, v26, v27 offset1:1
	v_add_u32_e32 v2, 0x1c78, v78
	ds_write2_b32 v2, v28, v29 offset1:1
	v_add_u32_e32 v2, 0x2080, v78
	s_waitcnt vmcnt(7)
	ds_write2_b32 v2, v58, v59 offset1:1
	v_add_u32_e32 v2, 0x2088, v78
	ds_write2_b32 v2, v60, v61 offset1:1
	v_add_u32_e32 v2, 0x2490, v78
	s_waitcnt vmcnt(6)
	ds_write2_b32 v2, v50, v51 offset1:1
	v_add_u32_e32 v2, 0x2498, v78
	ds_write2_b32 v2, v52, v53 offset1:1
	v_add_u32_e32 v2, 0x28a0, v78
	s_waitcnt vmcnt(5)
	ds_write2_b32 v2, v62, v63 offset1:1
	v_add_u32_e32 v2, 0x28a8, v78
	ds_write2_b32 v2, v64, v65 offset1:1
	v_add_u32_e32 v2, 0x2cb0, v78
	s_waitcnt vmcnt(4)
	ds_write2_b32 v2, v54, v55 offset1:1
	v_add_u32_e32 v2, 0x2cb8, v78
	ds_write2_b32 v2, v56, v57 offset1:1
	v_add_u32_e32 v2, 0x30c0, v78
	s_waitcnt vmcnt(3)
	ds_write2_b32 v2, v46, v47 offset1:1
	v_add_u32_e32 v2, 0x30c8, v78
	ds_write2_b32 v2, v48, v49 offset1:1
	v_add_u32_e32 v2, 0x34d0, v78
	s_waitcnt vmcnt(2)
	ds_write2_b32 v2, v42, v43 offset1:1
	v_add_u32_e32 v2, 0x34d8, v78
	ds_write2_b32 v2, v44, v45 offset1:1
	v_add_u32_e32 v2, 0x38e0, v78
	s_waitcnt vmcnt(1)
	ds_write2_b32 v2, v38, v39 offset1:1
	v_add_u32_e32 v2, 0x38e8, v78
	ds_write2_b32 v2, v40, v41 offset1:1
	v_add_u32_e32 v2, 0x3cf0, v78
	s_waitcnt vmcnt(0)
	ds_write2_b32 v2, v34, v35 offset1:1
	v_add_u32_e32 v2, 0x3cf8, v78
	ds_write2_b32 v2, v36, v37 offset1:1
	s_waitcnt lgkmcnt(0)
	v_add_u32_e32 v26, 0x400, v74
	s_ashr_i32 s31, s30, 31
	ds_read2_b32 v[6:7], v74 offset0:65 offset1:73
	ds_read2_b32 v[8:9], v74 offset1:8
	ds_read2_b32 v[10:11], v74 offset0:130 offset1:138
	ds_read2_b32 v[12:13], v74 offset0:195 offset1:203
	ds_read2_b32 v[14:15], v26 offset0:4 offset1:12
	ds_read2_b32 v[16:17], v26 offset0:69 offset1:77
	ds_read2_b32 v[18:19], v26 offset0:134 offset1:142
	ds_read2_b32 v[20:21], v26 offset0:199 offset1:207
	s_sub_i32 s10, s7, 32
	s_lshl_b64 s[8:9], s[30:31], 1
	s_add_u32 s4, s4, s8
	s_addc_u32 s5, s5, s9
	v_add_u32_e32 v27, s0, v71
	v_lshl_add_u64 v[22:23], s[4:5], 0, v[66:67]
	v_mad_i64_i32 v[24:25], s[4:5], s6, v27, 0
	s_waitcnt lgkmcnt(6)
	v_cvt_pk_bf16_f32 v2, v8, v6
	s_waitcnt lgkmcnt(4)
	v_cvt_pk_bf16_f32 v3, v10, v12
	s_waitcnt lgkmcnt(2)
	v_cvt_pk_bf16_f32 v4, v14, v16
	s_waitcnt lgkmcnt(0)
; __device__ __forceinline__ unsigned cvt_pk_bf16(float lo, float hi) { const f32x2 v = {lo, hi}; const bf16x2_t b = __builtin_convertvector(v, bf16x2_t); return __builtin_bit_cast(unsigned, b); }
; #define LAS __attribute__((address_space(3)))
; __device__ __forceinline__ void transpose_item(const float* W, int K, int N, const float* gain, bf16_t* WT, int k0, int n0, int drowA, int drowB, LAS float* scr, int lane) {
;     ...
;     for (int j = 0; j < 8; ++j) { const int n = (lane >> 3) + 8 * j; const LAS float* s = scr + (8 * c) * 65 + n;
;         u32x4 o; o.x = pg8::cvt_pk_bf16(s[0 * 65], s[1 * 65]); o.y = pg8::cvt_pk_bf16(s[2 * 65], s[3 * 65]); o.z = pg8::cvt_pk_bf16(s[4 * 65], s[5 * 65]); o.w = pg8::cvt_pk_bf16(s[6 * 65], s[7 * 65]);
;         const int drow = j < 4 ? drowA + n : drowB + n - 32;
;         *(u32x4*)(WT + (size_t)drow * K + k0 + 8 * c) = o; }
	v_cvt_pk_bf16_f32 v5, v18, v20
	v_lshl_add_u64 v[24:25], v[24:25], 1, v[22:23]
	global_store_dwordx4 v[24:25], v[2:5], off sc1
	v_add_u32_e32 v6, 8, v27
	v_readlane_b32 s0, v250, 20
	v_cvt_pk_bf16_f32 v2, v9, v7
	v_cvt_pk_bf16_f32 v3, v11, v13
	v_cvt_pk_bf16_f32 v4, v15, v17
	v_cvt_pk_bf16_f32 v5, v19, v21
	ds_read2_b32 v[8:9], v74 offset0:16 offset1:24
	ds_read2_b32 v[10:11], v74 offset0:81 offset1:89
	ds_read2_b32 v[12:13], v74 offset0:146 offset1:154
	ds_read2_b32 v[14:15], v74 offset0:211 offset1:219
	ds_read2_b32 v[16:17], v26 offset0:20 offset1:28
	ds_read2_b32 v[18:19], v26 offset0:85 offset1:93
	ds_read2_b32 v[20:21], v26 offset0:150 offset1:158
	ds_read2_b32 v[24:25], v26 offset0:215 offset1:223
	v_mad_i64_i32 v[6:7], s[4:5], s6, v6, 0
	v_lshl_add_u64 v[6:7], v[6:7], 1, v[22:23]
	global_store_dwordx4 v[6:7], v[2:5], off sc1
	v_add_u32_e32 v6, 16, v27
	v_mad_i64_i32 v[6:7], s[4:5], s6, v6, 0
	s_waitcnt lgkmcnt(6)
	v_cvt_pk_bf16_f32 v2, v8, v10
	s_waitcnt lgkmcnt(4)
	v_cvt_pk_bf16_f32 v3, v12, v14
	s_waitcnt lgkmcnt(2)
	v_cvt_pk_bf16_f32 v4, v16, v18
	s_waitcnt lgkmcnt(0)
	v_cvt_pk_bf16_f32 v5, v20, v24
	v_lshl_add_u64 v[6:7], v[6:7], 1, v[22:23]
	global_store_dwordx4 v[6:7], v[2:5], off sc1
	v_add_u32_e32 v6, 24, v27
	v_mad_i64_i32 v[6:7], s[4:5], s6, v6, 0
	v_cvt_pk_bf16_f32 v2, v9, v11
	v_cvt_pk_bf16_f32 v3, v13, v15
	v_cvt_pk_bf16_f32 v4, v17, v19
	v_cvt_pk_bf16_f32 v5, v21, v25
	ds_read2_b32 v[8:9], v74 offset0:32 offset1:40
	ds_read2_b32 v[10:11], v74 offset0:97 offset1:105
	ds_read2_b32 v[12:13], v74 offset0:162 offset1:170
	ds_read2_b32 v[14:15], v74 offset0:227 offset1:235
	ds_read2_b32 v[16:17], v26 offset0:36 offset1:44
	ds_read2_b32 v[18:19], v26 offset0:101 offset1:109
	ds_read2_b32 v[20:21], v26 offset0:166 offset1:174
	ds_read2_b32 v[24:25], v26 offset0:231 offset1:239
	v_lshl_add_u64 v[6:7], v[6:7], 1, v[22:23]
	global_store_dwordx4 v[6:7], v[2:5], off sc1
	v_add_u32_e32 v6, s7, v71
	v_mad_i64_i32 v[6:7], s[4:5], s6, v6, 0
	s_waitcnt lgkmcnt(6)
	v_cvt_pk_bf16_f32 v2, v8, v10
	s_waitcnt lgkmcnt(4)
	v_cvt_pk_bf16_f32 v3, v12, v14
	s_waitcnt lgkmcnt(2)
	v_cvt_pk_bf16_f32 v4, v16, v18
	s_waitcnt lgkmcnt(0)
	v_cvt_pk_bf16_f32 v5, v20, v24
	v_lshl_add_u64 v[6:7], v[6:7], 1, v[22:23]
	global_store_dwordx4 v[6:7], v[2:5], off sc1
	v_add_u32_e32 v6, s10, v75
	v_mad_i64_i32 v[6:7], s[4:5], s6, v6, 0
	v_cvt_pk_bf16_f32 v2, v9, v11
	v_cvt_pk_bf16_f32 v3, v13, v15
	v_cvt_pk_bf16_f32 v4, v17, v19
	v_cvt_pk_bf16_f32 v5, v21, v25
	ds_read2_b32 v[8:9], v74 offset0:48 offset1:56
	ds_read2_b32 v[10:11], v74 offset0:113 offset1:121
	ds_read2_b32 v[12:13], v74 offset0:178 offset1:186
	ds_read2_b32 v[14:15], v74 offset0:243 offset1:251
	ds_read2_b32 v[16:17], v26 offset0:52 offset1:60
	ds_read2_b32 v[18:19], v26 offset0:117 offset1:125
	ds_read2_b32 v[20:21], v26 offset0:182 offset1:190
	ds_read2_b32 v[24:25], v26 offset0:247 offset1:255
	v_lshl_add_u64 v[6:7], v[6:7], 1, v[22:23]
	global_store_dwordx4 v[6:7], v[2:5], off sc1
	v_add_u32_e32 v6, s10, v76
	v_mad_i64_i32 v[6:7], s[4:5], s6, v6, 0
	s_waitcnt lgkmcnt(6)
	v_cvt_pk_bf16_f32 v2, v8, v10
	s_waitcnt lgkmcnt(4)
	v_cvt_pk_bf16_f32 v3, v12, v14
	s_waitcnt lgkmcnt(2)
	v_cvt_pk_bf16_f32 v4, v16, v18
	s_waitcnt lgkmcnt(0)
	v_cvt_pk_bf16_f32 v5, v20, v24
	v_lshl_add_u64 v[6:7], v[6:7], 1, v[22:23]
	global_store_dwordx4 v[6:7], v[2:5], off sc1
	v_add_u32_e32 v6, s10, v77
	v_mad_i64_i32 v[6:7], s[4:5], s6, v6, 0
	v_cvt_pk_bf16_f32 v2, v9, v11
	v_cvt_pk_bf16_f32 v3, v13, v15
	v_cvt_pk_bf16_f32 v4, v17, v19
	v_cvt_pk_bf16_f32 v5, v21, v25
	v_lshl_add_u64 v[6:7], v[6:7], 1, v[22:23]
	global_store_dwordx4 v[6:7], v[2:5], off sc1
	s_add_i32 s48, s48, s0
	s_waitcnt lgkmcnt(0)
	s_add_i32 s50, s50, s0
	s_add_i32 s0, s48, 0x4b80
	s_cmpk_gt_i32 s0, 0x4eff
	s_cbranch_scc1 .LBB0_56
